# attention: work-queue atomic issued before the dispatch barrier; item epilogue stores widened (permlane16_swap pairs -> dwordx4) for the shared tail, MLA and NA first halves
# speedup vs baseline: 1.0066x; 1.0029x over previous
; template <int K> __device__ __forceinline__ float swz(float v) { return __int_as_float(__builtin_amdgcn_ds_swizzle(__float_as_int(v), (K << 10) | 0x1f)); }
; __device__ __forceinline__ float x32_sum(float v) { auto r = __builtin_amdgcn_permlane32_swap(__float_as_uint(v), __float_as_uint(v), false, false); return __uint_as_float(r[0]) + __uint_as_float(r[1]); }
; __device__ __forceinline__ unsigned cvt_pk_bf16(float lo, float hi) { const f32x2c f = {lo, hi}; return __builtin_bit_cast(unsigned, __builtin_convertvector(f, bf16x2c)); }
; __device__ __forceinline__ void na_item(unsigned char* smem, const bf16_t* U, const float* rpb_l, bf16_t* O, int b, int rp, int hp, float shift) {
;     ...
;     { float l = lA; l += swz<16>(l); l = x32_sum(l); const float inv = 1.0f / l;
;       bf16_t* orow = O + qrowA * OW + h * 64 + fq * 4;
; #pragma unroll
;       for (int dg = 0; dg < 4; ++dg) { u32x2_t w; w.x = pg8::cvt_pk_bf16(oA[dg][0] * inv, oA[dg][1] * inv); w.y = pg8::cvt_pk_bf16(oA[dg][2] * inv, oA[dg][3] * inv); *(u32x2_t*)(orow + dg * 16) = w; } }
;     { float l = lB; l += swz<16>(l); l = x32_sum(l); const float inv = 1.0f / l;
;       bf16_t* orow = O + qrowB * OW + h * 64 + fq * 4;
; #pragma unroll
;       for (int dg = 0; dg < 4; ++dg) { u32x2_t w; w.x = pg8::cvt_pk_bf16(oB[dg][0] * inv, oB[dg][1] * inv); w.y = pg8::cvt_pk_bf16(oB[dg][2] * inv, oB[dg][3] * inv); *(u32x2_t*)(orow + dg * 16) = w; } }
.LBB0_820:
	ds_swizzle_b32 v14, v113 offset:swizzle(SWAP,16)
	v_mov_b32_e32 v75, v0
	s_waitcnt lgkmcnt(0)
	v_add_f32_e32 v14, v113, v14
	v_mov_b32_e32 v15, v14
	s_nop 1
	v_permlane32_swap_b32_e32 v14, v15
	v_add_f32_e32 v14, v14, v15
	v_div_scale_f32 v15, s[2:3], v14, v14, 1.0
	v_rcp_f32_e32 v16, v15
	s_nop 0
	v_fma_f32 v17, -v15, v16, 1.0
	v_fmac_f32_e32 v16, v17, v16
	v_div_scale_f32 v17, vcc, 1.0, v14, 1.0
	v_mul_f32_e32 v18, v17, v16
	v_fma_f32 v19, -v15, v18, v17
	v_fmac_f32_e32 v18, v19, v16
	v_fma_f32 v15, -v15, v18, v17
	v_div_fmas_f32 v15, v15, v16, v18
	v_mov_b64_e32 v[16:17], s[66:67]
	v_div_fixup_f32 v14, v15, v14, 1.0
	v_mad_u64_u32 v[16:17], s[2:3], v1, s93, v[16:17]
	v_lshl_add_u64 v[16:17], v[106:107], 1, v[16:17]
	v_pk_mul_f32 v[18:19], v[70:71], v[14:15] op_sel_hi:[1,0]
	v_pk_mul_f32 v[20:21], v[72:73], v[14:15] op_sel_hi:[1,0]
	v_lshl_add_u64 v[16:17], v[74:75], 1, v[16:17]
	v_cvt_pk_bf16_f32 v18, v18, v19
	v_cvt_pk_bf16_f32 v19, v20, v21
	ds_swizzle_b32 v1, v112 offset:swizzle(SWAP,16)
	global_store_dwordx2 v[16:17], v[18:19], off
	v_pk_mul_f32 v[18:19], v[66:67], v[14:15] op_sel_hi:[1,0]
	v_pk_mul_f32 v[20:21], v[68:69], v[14:15] op_sel_hi:[1,0]
	v_cvt_pk_bf16_f32 v18, v18, v19
	v_cvt_pk_bf16_f32 v19, v20, v21
	global_store_dwordx2 v[16:17], v[18:19], off offset:32
	v_pk_mul_f32 v[18:19], v[62:63], v[14:15] op_sel_hi:[1,0]
	v_pk_mul_f32 v[20:21], v[64:65], v[14:15] op_sel_hi:[1,0]
	v_cvt_pk_bf16_f32 v18, v18, v19
	v_cvt_pk_bf16_f32 v19, v20, v21
	global_store_dwordx2 v[16:17], v[18:19], off offset:64
	v_pk_mul_f32 v[18:19], v[58:59], v[14:15] op_sel_hi:[1,0]
	v_pk_mul_f32 v[14:15], v[60:61], v[14:15] op_sel_hi:[1,0]
	s_waitcnt lgkmcnt(0)
	v_add_f32_e32 v1, v112, v1
	v_cvt_pk_bf16_f32 v18, v18, v19
	v_cvt_pk_bf16_f32 v19, v14, v15
	v_mov_b32_e32 v14, v1
	s_nop 1
	v_permlane32_swap_b32_e32 v1, v14
	v_add_f32_e32 v1, v1, v14
	v_div_scale_f32 v14, s[2:3], v1, v1, 1.0
	v_rcp_f32_e32 v15, v14
	global_store_dwordx2 v[16:17], v[18:19], off offset:96
	s_mov_b64 s[2:3], 0x28000
	v_fma_f32 v18, -v14, v15, 1.0
	v_fmac_f32_e32 v15, v18, v15
	v_div_scale_f32 v18, vcc, 1.0, v1, 1.0
	v_mul_f32_e32 v19, v18, v15
	v_fma_f32 v20, -v14, v19, v18
	v_fmac_f32_e32 v19, v20, v15
	v_fma_f32 v14, -v14, v19, v18
	v_div_fmas_f32 v14, v14, v15, v19
	v_div_fixup_f32 v18, v14, v1, 1.0
	v_lshl_add_u64 v[20:21], v[16:17], 0, s[2:3]
	v_pk_mul_f32 v[14:15], v[54:55], v[18:19] op_sel_hi:[1,0]
	v_pk_mul_f32 v[22:23], v[56:57], v[18:19] op_sel_hi:[1,0]
	v_add_co_u32_e32 v16, vcc, 0x28000, v16
	v_cvt_pk_bf16_f32 v148, v14, v15
	v_cvt_pk_bf16_f32 v149, v22, v23
	v_addc_co_u32_e32 v17, vcc, 0, v17, vcc
.LBB0_821:
	v_mov_b32_e32 v19, v18
	v_pk_mul_f32 v[2:3], v[2:3], v[18:19]
	v_pk_mul_f32 v[4:5], v[4:5], v[18:19]
	v_cvt_pk_bf16_f32 v150, v2, v3
	v_cvt_pk_bf16_f32 v151, v4, v5
	v_pk_mul_f32 v[2:3], v[18:19], v[6:7]
	v_pk_mul_f32 v[4:5], v[18:19], v[8:9]
	v_cvt_pk_bf16_f32 v80, v2, v3
	v_cvt_pk_bf16_f32 v81, v4, v5
	v_pk_mul_f32 v[2:3], v[18:19], v[10:11]
	v_pk_mul_f32 v[4:5], v[18:19], v[12:13]
	v_cvt_pk_bf16_f32 v82, v2, v3
	v_cvt_pk_bf16_f32 v83, v4, v5
	v_and_b32_e32 v84, 16, v253
	v_lshrrev_b32_e32 v86, 1, v84
	v_add_u32_e32 v84, v84, v86
	v_mov_b32_e32 v85, 0
	v_permlane16_swap_b32_e32 v148, v150
	v_permlane16_swap_b32_e32 v149, v151
	v_permlane16_swap_b32_e32 v80, v82
	v_permlane16_swap_b32_e32 v81, v83
	v_lshl_add_u64 v[20:21], v[20:21], 0, v[84:85]
	s_mov_b64 s[2:3], 0
	global_store_dwordx4 v[20:21], v[148:151], off
	global_store_dwordx4 v[20:21], v[80:83], off offset:64

; __device__ __forceinline__ int otid() { int t = threadIdx.x; asm volatile("" : "+v"(t)); return t; }
; #define LASP __attribute__((address_space(3)))
; __device__ __forceinline__ void p4_attn(const Params& P, int l, bool last, unsigned char* smem) {
;     ...
;             volatile LASP unsigned* slot = (volatile LASP unsigned*)((LASP unsigned char*)smem + 131072 + 8);
;             __syncthreads();
;             if (otid() == 0) *slot = __hip_atomic_fetch_add((unsigned*)(PWS + WS_Q) + (size_t)(l * 8 + q) * 64, 1u, __ATOMIC_RELAXED, __HIP_MEMORY_SCOPE_AGENT);
;             __syncthreads();
;             const int i = __builtin_amdgcn_readfirstlane((int)*slot);
.LBB0_823:
	v_mov_b32_e32 v1, v253
	s_nop 0
	v_cmp_eq_u32_e32 vcc, 0, v1
	s_and_saveexec_b64 s[2:3], vcc
	s_cbranch_execz .Ldisp_pre
	s_mov_b64 s[20:21], exec
	v_mbcnt_lo_u32_b32 v1, s20, 0
	v_mbcnt_hi_u32_b32 v1, s21, v1
	v_cmp_eq_u32_e32 vcc, 0, v1
	s_and_saveexec_b64 s[16:17], vcc
	s_cbranch_execz .LBB0_826
	s_bcnt1_i32_b64 s5, s[20:21]
	v_mov_b32_e32 v2, s5
	global_atomic_add v2, v0, v2, s[24:25] sc0

; __device__ __forceinline__ int otid() { int t = threadIdx.x; asm volatile("" : "+v"(t)); return t; }
; __device__ __forceinline__ void p4_attn(const Params& P, int l, bool last, unsigned char* smem) {
;     ...
;             if (otid() == 0) *slot = __hip_atomic_fetch_add((unsigned*)(PWS + WS_Q) + (size_t)(l * 8 + q) * 64, 1u, __ATOMIC_RELAXED, __HIP_MEMORY_SCOPE_AGENT);
;             __syncthreads();
;             const int i = __builtin_amdgcn_readfirstlane((int)*slot);
.Ldisp_pre:
	s_or_b64 exec, exec, s[2:3]
	s_barrier
	v_cmp_eq_u32_e32 vcc, 0, v253
	s_and_saveexec_b64 s[2:3], vcc
	s_cbranch_execz .LBB0_827
	s_waitcnt vmcnt(0)
	v_readfirstlane_b32 s5, v2
	v_mov_b32_e32 v2, s94
	s_nop 0
	v_add_u32_e32 v1, s5, v1
	ds_write_b32 v2, v1

; template <int K> __device__ __forceinline__ float swz(float v) { return __int_as_float(__builtin_amdgcn_ds_swizzle(__float_as_int(v), (K << 10) | 0x1f)); }
; __device__ __forceinline__ float x32_sum(float v) { auto r = __builtin_amdgcn_permlane32_swap(__float_as_uint(v), __float_as_uint(v), false, false); return __uint_as_float(r[0]) + __uint_as_float(r[1]); }
; __device__ __forceinline__ int otid() { int t = threadIdx.x; asm volatile("" : "+v"(t)); return t; }
; #define LASP __attribute__((address_space(3)))
; template <int DQK>
; __device__ __forceinline__ void flash_item(unsigned char* smem, const bf16_t* Q, int qs, const bf16_t* K0, const bf16_t* V0, int n0, const bf16_t* K1, const bf16_t* V1, int n1, int ks, int vs, bf16_t* Oo, int os, float shift) {
;     ...
;     const int tid = otid(), lane = tid & 63, wave = tid >> 6, fr = lane & 15, fq = lane >> 4;
;     LASP unsigned char* ls = (LASP unsigned char*)smem;
;     bf16x8_t qf[2][NKK];
; #pragma unroll
;     for (int qg = 0; qg < 2; ++qg)
; #pragma unroll
;         for (int kk = 0; kk < NKK; ++kk) qf[qg][kk] = *(const bf16x8_t*)(Q + (size_t)(wave * 32 + qg * 16 + fr) * qs + kk * 32 + fq * 8);
;     f32x4_t o[4][2];
; #pragma unroll
;     for (int dg = 0; dg < 4; ++dg) { o[dg][0] = (f32x4_t){0.f, 0.f, 0.f, 0.f}; o[dg][1] = (f32x4_t){0.f, 0.f, 0.f, 0.f}; }
;     float lsum[2] = {0.f, 0.f};
;     const float nsh = -shift;
;     const int ntiles = (n0 + n1) / KT;
;     u32x4_t kreg[NKC], vreg[NVC];
;     ...
;     FL_LOAD(0);
;     for (int t = 0; t < ntiles; ++t) {
;         __syncthreads();
; #pragma unroll
;         for (int c = 0; c < NKC; ++c) *(LASP u32x4_t*)(ls + (tid >> 2) * KR + ((tid & 3) + 4 * c) * 16) = kreg[c];
; #pragma unroll
;         for (int c = 0; c < NVC; ++c) *(LASP u32x4_t*)(ls + VOFF + ((tid >> 3) + 64 * c) * VR + (tid & 7) * 16) = vreg[c];
;         __syncthreads();
;     ...
;     for (int qg = 0; qg < 2; ++qg) {
;         float l = lsum[qg]; l += swz<16>(l); l = x32_sum(l);
;         const float inv = 1.0f / l;
;         bf16_t* orow = Oo + (size_t)(wave * 32 + qg * 16 + fr) * os + fq * 4;
; #pragma unroll
;         for (int dg = 0; dg < 4; ++dg) {
;             u32x2_t w; w.x = pg8::cvt_pk_bf16(o[dg][qg][0] * inv, o[dg][qg][1] * inv); w.y = pg8::cvt_pk_bf16(o[dg][qg][2] * inv, o[dg][qg][3] * inv);
;             *(u32x2_t*)(orow + dg * 16) = w;
;         }
.LBB0_834:
	s_setprio 0
	ds_swizzle_b32 v1, v157 offset:swizzle(SWAP,16)
	s_mul_i32 s2, s28, 0xa00
	s_mul_hi_u32 s5, s3, 0xa00
	s_add_i32 s5, s5, s2
	s_mul_i32 s2, s3, 0xa00
	s_waitcnt lgkmcnt(0)
	v_add_f32_e32 v1, v157, v1
	v_mov_b32_e32 v14, v1
	s_nop 1
	v_permlane32_swap_b32_e32 v1, v14
	v_add_f32_e32 v1, v1, v14
	v_div_scale_f32 v16, s[16:17], v1, v1, 1.0
	v_rcp_f32_e32 v17, v16
	s_add_u32 s2, s66, s2
	s_addc_u32 s3, s67, s5
	s_add_u32 s2, s2, s20
	v_fma_f32 v18, -v16, v17, 1.0
	v_fmac_f32_e32 v17, v18, v17
	v_div_scale_f32 v18, vcc, 1.0, v1, 1.0
	v_mul_f32_e32 v19, v18, v17
	v_fma_f32 v20, -v16, v19, v18
	v_fmac_f32_e32 v19, v20, v17
	v_fma_f32 v16, -v16, v19, v18
	v_div_fmas_f32 v16, v16, v17, v19
	s_addc_u32 s3, s3, s21
	v_lshlrev_b32_e32 v14, 1, v145
	v_mov_b32_e32 v15, v0
	v_div_fixup_f32 v16, v16, v1, 1.0
	v_lshl_add_u64 v[14:15], s[2:3], 0, v[14:15]
	v_pk_mul_f32 v[20:21], v[62:63], v[16:17] op_sel_hi:[1,0]
	v_pk_mul_f32 v[22:23], v[64:65], v[16:17] op_sel_hi:[1,0]
	ds_swizzle_b32 v1, v156 offset:swizzle(SWAP,16)
	v_mad_i64_i32 v[18:19], s[2:3], v144, s93, v[14:15]
	v_cvt_pk_bf16_f32 v88, v20, v21
	v_cvt_pk_bf16_f32 v89, v22, v23
	v_pk_mul_f32 v[20:21], v[74:75], v[16:17] op_sel_hi:[1,0]
	v_pk_mul_f32 v[22:23], v[76:77], v[16:17] op_sel_hi:[1,0]
	v_cvt_pk_bf16_f32 v90, v20, v21
	v_cvt_pk_bf16_f32 v91, v22, v23
	v_pk_mul_f32 v[20:21], v[70:71], v[16:17] op_sel_hi:[1,0]
	v_pk_mul_f32 v[22:23], v[72:73], v[16:17] op_sel_hi:[1,0]
	v_cvt_pk_bf16_f32 v92, v20, v21
	v_cvt_pk_bf16_f32 v93, v22, v23
	s_waitcnt lgkmcnt(0)
	v_add_f32_e32 v1, v156, v1
	v_pk_mul_f32 v[20:21], v[66:67], v[16:17] op_sel_hi:[1,0]
	v_mov_b32_e32 v17, v1
	s_nop 1
	v_permlane32_swap_b32_e32 v1, v17
	v_add_f32_e32 v1, v1, v17
	v_div_scale_f32 v22, s[2:3], v1, v1, 1.0
	v_rcp_f32_e32 v23, v22
	v_pk_mul_f32 v[16:17], v[68:69], v[16:17] op_sel_hi:[1,0]
	v_cvt_pk_bf16_f32 v94, v20, v21
	v_cvt_pk_bf16_f32 v95, v16, v17
	v_fma_f32 v16, -v22, v23, 1.0
	v_fmac_f32_e32 v23, v16, v23
	v_div_scale_f32 v16, vcc, 1.0, v1, 1.0
	v_mul_f32_e32 v17, v16, v23
	v_and_b32_e32 v96, 16, v253
	v_lshrrev_b32_e32 v98, 1, v96
	v_add_u32_e32 v96, v96, v98
	v_mov_b32_e32 v97, 0
	v_permlane16_swap_b32_e32 v88, v90
	v_permlane16_swap_b32_e32 v89, v91
	v_permlane16_swap_b32_e32 v92, v94
	v_permlane16_swap_b32_e32 v93, v95
	v_lshl_add_u64 v[18:19], v[18:19], 0, v[96:97]
	global_store_dwordx4 v[18:19], v[88:91], off offset:768
	global_store_dwordx4 v[18:19], v[92:95], off offset:832
	v_fma_f32 v18, -v22, v17, v16
	v_fmac_f32_e32 v17, v18, v23
	v_fma_f32 v16, -v22, v17, v16
	v_div_fmas_f32 v16, v16, v23, v17
	v_div_fixup_f32 v18, v16, v1, 1.0
	v_mad_i64_i32 v[14:15], s[2:3], v142, s93, v[14:15]
	v_pk_mul_f32 v[16:17], v[58:59], v[18:19] op_sel_hi:[1,0]
	v_pk_mul_f32 v[22:23], v[60:61], v[18:19] op_sel_hi:[1,0]
	s_mov_b64 s[2:3], 0x300
	v_cvt_pk_bf16_f32 v148, v16, v17
	v_cvt_pk_bf16_f32 v149, v22, v23
	v_lshl_add_u64 v[20:21], v[14:15], 0, s[2:3]
	s_mov_b64 s[2:3], 0
.LBB0_835:
	s_and_b64 vcc, exec, s[2:3]
	s_cbranch_vccz .LBB0_837
	s_add_i32 s2, s11, s13
	s_mul_hi_u32 s3, s2, 0xaaaaaaab
	s_lshr_b32 s3, s3, 2
	s_mul_i32 s5, s3, 6
	s_lshl_b32 s3, s3, 8
	s_add_i32 s3, s3, 0x8000
	s_sub_i32 s2, s2, s5
	s_mul_i32 s16, s3, 0x1200
	s_mul_hi_u32 s5, s3, 0x1200
	s_add_u32 s16, s68, s16
	s_addc_u32 s5, s69, s5
	s_lshl_b32 s2, s2, 7
	s_add_u32 s16, s16, s2
	v_mov_b32_e32 v70, v253
	s_addc_u32 s17, s5, 0
	v_mov_b64_e32 v[2:3], s[16:17]
	v_lshlrev_b32_e32 v1, 3, v70
	s_waitcnt vmcnt(9)
	v_ashrrev_i32_e32 v36, 2, v70
	v_and_b32_e32 v124, 24, v1
	v_mad_i64_i32 v[2:3], s[18:19], v36, s90, v[2:3]
	v_lshlrev_b32_e32 v4, 1, v124
	v_mov_b32_e32 v5, v0
	v_lshlrev_b32_e32 v37, 4, v70
	v_lshl_add_u64 v[58:59], v[2:3], 0, v[4:5]
	v_and_b32_e32 v2, 0x70, v37
	v_mov_b32_e32 v3, v0
	global_load_dwordx4 v[18:21], v[58:59], off offset:768
	global_load_dwordx4 v[22:25], v[58:59], off offset:832
	v_ashrrev_i32_e32 v64, 3, v70
	v_lshl_add_u64 v[60:61], s[16:17], 0, v[2:3]
	v_mad_i64_i32 v[4:5], s[18:19], v64, s90, v[60:61]
	v_add_u32_e32 v65, 64, v64
	global_load_dwordx4 v[26:29], v[4:5], off offset:1536
	v_mad_i64_i32 v[4:5], s[18:19], v65, s90, v[60:61]
	global_load_dwordx4 v[30:33], v[4:5], off offset:1536
	v_and_b32_e32 v3, 15, v70
	v_bfe_u32 v1, v70, 4, 2
	v_ashrrev_i32_e32 v4, 1, v70
	v_mov_b32_e32 v216, v211
	v_and_or_b32 v211, v4, s95, v3
	v_lshlrev_b32_e32 v4, 4, v1
	v_mov_b32_e32 v5, v0
	v_lshl_add_u64 v[6:7], s[16:17], 0, v[4:5]
	v_or_b32_e32 v227, 16, v211
	v_mad_i64_i32 v[8:9], s[16:17], v211, s90, v[6:7]
	v_mad_i64_i32 v[34:35], s[16:17], v227, s90, v[6:7]
	global_load_dwordx4 v[10:13], v[8:9], off
	global_load_dwordx4 v[14:17], v[34:35], off
	v_mul_lo_u32 v5, v36, s89
	v_and_b32_e32 v6, 48, v37
	v_mul_lo_u32 v7, v64, s89
	v_mul_u32_u24_e32 v3, 0x90, v3
	v_add3_u32 v63, 0, v5, v6
	v_add3_u32 v62, 0, v2, v7
	v_add3_u32 v71, 0, v4, v3
	global_load_dwordx4 v[6:9], v[8:9], off offset:64
	s_nop 0
	global_load_dwordx4 v[2:5], v[34:35], off offset:64
	s_barrier
	s_mov_b64 s[16:17], 0x90600
	v_lshl_add_u64 v[60:61], v[60:61], 0, s[16:17]
	v_mad_i64_i32 v[146:147], s[16:17], v65, s90, v[60:61]
	s_mov_b32 s5, 0x90000
	v_lshlrev_b32_e32 v204, 3, v1
	v_mov_b32_e32 v205, v0
	s_waitcnt vmcnt(7)
	ds_write_b128 v63, v[18:21]
	s_waitcnt vmcnt(6)
	ds_write_b128 v63, v[22:25] offset:64
	s_waitcnt vmcnt(5)
	ds_write_b128 v62, v[26:29] offset:32768
	s_waitcnt vmcnt(4)
	ds_write_b128 v62, v[30:33] offset:41984
	s_waitcnt lgkmcnt(0)
	s_barrier
; #define LASP __attribute__((address_space(3)))
; template <int DQK>
; __device__ __forceinline__ void flash_item(unsigned char* smem, const bf16_t* Q, int qs, const bf16_t* K0, const bf16_t* V0, int n0, const bf16_t* K1, const bf16_t* V1, int n1, int ks, int vs, bf16_t* Oo, int os, float shift) {
;     ...
;         f32x4_t s[NKG][2];
; #pragma unroll
;         for (int kg = 0; kg < NKG; ++kg) { s[kg][0] = (f32x4_t){nsh, nsh, nsh, nsh}; s[kg][1] = (f32x4_t){nsh, nsh, nsh, nsh}; }
; #pragma unroll
;         for (int kk = 0; kk < NKK; ++kk) {
; #pragma unroll
;             for (int kg = 0; kg < NKG; ++kg) {
;                 const bf16x8_t kf = *(const LASP bf16x8_t*)(ls + (kg * 16 + fr) * KR + (kk * 32 + fq * 8) * 2);
;                 s[kg][0] = __builtin_amdgcn_mfma_f32_16x16x32_bf16(kf, qf[0][kk], s[kg][0], 0, 0, 0);
;                 s[kg][1] = __builtin_amdgcn_mfma_f32_16x16x32_bf16(kf, qf[1][kk], s[kg][1], 0, 0, 0);
;             }
;             asm volatile("" ::: "memory");
;         }
;         if (t + 1 < ntiles) FL_LOAD((t + 1) * KT);
; #pragma unroll
;         for (int qg = 0; qg < 2; ++qg) {
;             float ps = 0.f;
; #pragma unroll
;             for (int kg = 0; kg < NKG; ++kg)
; #pragma unroll
;                 for (int j = 0; j < 4; ++j) { const float p = __builtin_amdgcn_exp2f(s[kg][qg][j]); s[kg][qg][j] = p; ps += p; }
;             lsum[qg] += ps;
;         }
; #pragma unroll
;         for (int kp = 0; kp < NKP; ++kp) {
;             bf16x8_t pb[2];
; #pragma unroll
;             for (int qg = 0; qg < 2; ++qg) {
;                 const f32x4_t a = s[2 * kp][qg], b = s[2 * kp + 1][qg];
;                 u32x4_t pk; pk.x = pg8::cvt_pk_bf16(a[0], a[1]); pk.y = pg8::cvt_pk_bf16(a[2], a[3]); pk.z = pg8::cvt_pk_bf16(b[0], b[1]); pk.w = pg8::cvt_pk_bf16(b[2], b[3]);
;                 pb[qg] = __builtin_bit_cast(bf16x8_t, pk);
;             }
; #pragma unroll
;             for (int dg = 0; dg < 4; ++dg) {
;                 LASP unsigned char* va = ls + VOFF + (32 * kp + 4 * fq + (fr >> 2)) * VR + (16 * dg + 4 * (fr & 3)) * 2;
;                 const s16x4 v0 = __builtin_amdgcn_ds_read_tr16_b64_v4i16((LASP s16x4*)va);
;                 const s16x4 v1 = __builtin_amdgcn_ds_read_tr16_b64_v4i16((LASP s16x4*)(va + 16 * VR));
;                 const bf16x8_t vf = __builtin_shufflevector(v0, v1, 0, 1, 2, 3, 4, 5, 6, 7);
	ds_read_b128 v[54:57], v71 offset:9216
	v_mov_b64_e32 v[18:19], s[48:49]
	v_mov_b64_e32 v[20:21], s[50:51]
	ds_read_b128 v[22:25], v71
	ds_read_b128 v[30:33], v71 offset:2304
	s_waitcnt vmcnt(3) lgkmcnt(2)
	v_mfma_f32_16x16x32_bf16 v[66:69], v[54:57], v[10:13], v[18:21]
	ds_read_b128 v[38:41], v71 offset:4608
	ds_read_b128 v[46:49], v71 offset:6912
	s_waitcnt vmcnt(2)
	v_mfma_f32_16x16x32_bf16 v[72:75], v[54:57], v[14:17], v[18:21]
	ds_read_b128 v[54:57], v71 offset:11520
	s_waitcnt lgkmcnt(0)
	v_mfma_f32_16x16x32_bf16 v[76:79], v[54:57], v[10:13], v[18:21]
	v_mfma_f32_16x16x32_bf16 v[80:83], v[54:57], v[14:17], v[18:21]
	ds_read_b128 v[54:57], v71 offset:13824
	s_waitcnt lgkmcnt(0)
	v_mfma_f32_16x16x32_bf16 v[84:87], v[54:57], v[10:13], v[18:21]
	v_mfma_f32_16x16x32_bf16 v[88:91], v[54:57], v[14:17], v[18:21]
	ds_read_b128 v[54:57], v71 offset:16128
	s_waitcnt lgkmcnt(0)
	v_mfma_f32_16x16x32_bf16 v[92:95], v[54:57], v[10:13], v[18:21]
	v_mfma_f32_16x16x32_bf16 v[96:99], v[54:57], v[14:17], v[18:21]
	ds_read_b128 v[54:57], v71 offset:64
	v_mfma_f32_16x16x32_bf16 v[26:29], v[22:25], v[10:13], v[18:21]
	v_mfma_f32_16x16x32_bf16 v[22:25], v[22:25], v[14:17], v[18:21]
	s_waitcnt vmcnt(0) lgkmcnt(0)
	v_mfma_f32_16x16x32_bf16 v[104:107], v[54:57], v[2:5], v[22:25]
	v_mfma_f32_16x16x32_bf16 v[34:37], v[30:33], v[10:13], v[18:21]
	s_nop 4
	ds_read_b128 v[22:25], v71 offset:2368
	s_nop 0
	v_exp_f32_e32 v196, v105
	v_exp_f32_e32 v198, v106
	v_mfma_f32_16x16x32_bf16 v[30:33], v[30:33], v[14:17], v[18:21]
	v_exp_f32_e32 v188, v107
	s_nop 0
	v_cvt_pk_bf16_f32 v107, v198, v188
	s_waitcnt lgkmcnt(0)
	v_mfma_f32_16x16x32_bf16 v[108:111], v[22:25], v[6:9], v[34:37]
	v_mfma_f32_16x16x32_bf16 v[112:115], v[22:25], v[2:5], v[30:33]
	ds_read_b128 v[22:25], v71 offset:4672
	s_nop 5
	v_exp_f32_e32 v160, v108
	v_exp_f32_e32 v158, v109
	v_mfma_f32_16x16x32_bf16 v[42:45], v[38:41], v[10:13], v[18:21]
	v_bfe_u32 v30, v70, 2, 2
	v_exp_f32_e32 v164, v110
	v_exp_f32_e32 v162, v111
	v_mfma_f32_16x16x32_bf16 v[38:41], v[38:41], v[14:17], v[18:21]
	v_exp_f32_e32 v192, v112
	v_exp_f32_e32 v190, v113
	v_exp_f32_e32 v194, v114
	v_mfma_f32_16x16x32_bf16 v[100:103], v[54:57], v[6:9], v[26:29]
	v_exp_f32_e32 v200, v115
	v_cvt_pk_bf16_f32 v105, v164, v162
	v_cvt_pk_bf16_f32 v108, v192, v190
	s_waitcnt lgkmcnt(0)
	v_mfma_f32_16x16x32_bf16 v[116:119], v[22:25], v[6:9], v[42:45]
	v_cvt_pk_bf16_f32 v109, v194, v200
	s_nop 1
	v_exp_f32_e32 v142, v101
	v_exp_f32_e32 v156, v102
	v_mfma_f32_16x16x32_bf16 v[54:57], v[22:25], v[2:5], v[38:41]
	ds_read_b128 v[22:25], v71 offset:6976
	v_exp_f32_e32 v144, v103
	v_exp_f32_e32 v170, v116
	v_mfma_f32_16x16x32_bf16 v[50:53], v[46:49], v[10:13], v[18:21]
	v_cvt_pk_bf16_f32 v103, v156, v144
	s_nop 2
	v_exp_f32_e32 v202, v54
	v_mfma_f32_16x16x32_bf16 v[46:49], v[46:49], v[14:17], v[18:21]
	v_exp_f32_e32 v186, v55
	v_exp_f32_e32 v178, v56
	v_exp_f32_e32 v176, v57
	s_waitcnt lgkmcnt(0)
	v_mfma_f32_16x16x32_bf16 v[120:123], v[22:25], v[6:9], v[50:53]
	v_cvt_pk_bf16_f32 v138, v202, v186
	v_cvt_pk_bf16_f32 v139, v178, v176
	v_mfma_f32_16x16x32_bf16 v[50:53], v[22:25], v[2:5], v[46:49]
	ds_read_b128 v[22:25], v71 offset:9280
	s_waitcnt lgkmcnt(0)
	v_mfma_f32_16x16x32_bf16 v[66:69], v[22:25], v[6:9], v[66:69]
	s_nop 4
	v_exp_f32_e32 v180, v50
	v_exp_f32_e32 v174, v51
	v_exp_f32_e32 v128, v53
	v_mfma_f32_16x16x32_bf16 v[42:45], v[22:25], v[2:5], v[72:75]
	ds_read_b128 v[22:25], v71 offset:11584
	v_exp_f32_e32 v70, v67
	v_cvt_pk_bf16_f32 v140, v180, v174
	s_waitcnt lgkmcnt(0)
	v_mfma_f32_16x16x32_bf16 v[46:49], v[22:25], v[6:9], v[76:79]
	v_lshl_or_b32 v74, v1, 2, v30
	v_exp_f32_e32 v73, v100
	v_exp_f32_e32 v72, v68
	v_mfma_f32_16x16x32_bf16 v[38:41], v[22:25], v[2:5], v[80:83]
	ds_read_b128 v[22:25], v71 offset:13888
	v_exp_f32_e32 v75, v104
	v_exp_f32_e32 v76, v117
	s_waitcnt lgkmcnt(0)
	v_mfma_f32_16x16x32_bf16 v[34:37], v[22:25], v[6:9], v[84:87]
	v_exp_f32_e32 v80, v118
	v_exp_f32_e32 v78, v119
	s_nop 0
	v_exp_f32_e32 v84, v120
	v_mfma_f32_16x16x32_bf16 v[26:29], v[22:25], v[2:5], v[88:91]
	ds_read_b128 v[22:25], v71 offset:16192
	v_exp_f32_e32 v82, v121
	s_waitcnt lgkmcnt(0)
	v_mfma_f32_16x16x32_bf16 v[30:33], v[22:25], v[6:9], v[92:95]
	v_exp_f32_e32 v88, v122
	v_exp_f32_e32 v86, v123
	v_cvt_pk_bf16_f32 v102, v73, v142
	v_mfma_f32_16x16x32_bf16 v[22:25], v[22:25], v[2:5], v[96:99]
	v_cvt_pk_bf16_f32 v104, v160, v158
	v_exp_f32_e32 v118, v52
	v_cvt_pk_bf16_f32 v106, v75, v196
	v_exp_f32_e32 v96, v66
	v_mul_u32_u24_e32 v66, 0x90, v74
	v_add3_u32 v226, 0, v124, v66
	ds_read_b64_tr_b16 v[92:93], v226 offset:35072
	ds_read_b64_tr_b16 v[90:91], v226 offset:32768
	ds_read_b64_tr_b16 v[110:111], v226 offset:32800
	ds_read_b64_tr_b16 v[112:113], v226 offset:35104
	v_exp_f32_e32 v74, v69
	ds_read_b64_tr_b16 v[66:67], v226 offset:32832
	ds_read_b64_tr_b16 v[68:69], v226 offset:35136
	ds_read_b64_tr_b16 v[130:131], v226 offset:32864
	ds_read_b64_tr_b16 v[132:133], v226 offset:35168
	ds_read_b64_tr_b16 v[50:51], v226 offset:37376
	ds_read_b64_tr_b16 v[52:53], v226 offset:39680
	s_waitcnt lgkmcnt(8)
	v_mfma_f32_16x16x32_bf16 v[114:117], v[90:93], v[102:105], 0
	v_exp_f32_e32 v94, v46
	v_exp_f32_e32 v100, v48
	v_cvt_pk_bf16_f32 v141, v118, v128
	v_mfma_f32_16x16x32_bf16 v[120:123], v[90:93], v[106:109], 0
	v_exp_f32_e32 v92, v47
	v_exp_f32_e32 v184, v42
	v_exp_f32_e32 v182, v43
	s_waitcnt lgkmcnt(6)
	v_mfma_f32_16x16x32_bf16 v[124:127], v[110:113], v[102:105], 0
	v_exp_f32_e32 v168, v44
	v_exp_f32_e32 v166, v45
	v_exp_f32_e32 v172, v38
	v_mfma_f32_16x16x32_bf16 v[110:113], v[110:113], v[106:109], 0
	v_exp_f32_e32 v90, v35
	v_exp_f32_e32 v98, v36
	s_waitcnt lgkmcnt(4)
; __device__ __forceinline__ unsigned cvt_pk_bf16(float lo, float hi) { const f32x2c f = {lo, hi}; return __builtin_bit_cast(unsigned, __builtin_convertvector(f, bf16x2c)); }
; #define LASP __attribute__((address_space(3)))
; template <int DQK>
; __device__ __forceinline__ void flash_item(unsigned char* smem, const bf16_t* Q, int qs, const bf16_t* K0, const bf16_t* V0, int n0, const bf16_t* K1, const bf16_t* V1, int n1, int ks, int vs, bf16_t* Oo, int os, float shift) {
;     ...
;     FL_LOAD(0);
;     for (int t = 0; t < ntiles; ++t) {
;         __syncthreads();
; #pragma unroll
;         for (int c = 0; c < NKC; ++c) *(LASP u32x4_t*)(ls + (tid >> 2) * KR + ((tid & 3) + 4 * c) * 16) = kreg[c];
; #pragma unroll
;         for (int c = 0; c < NVC; ++c) *(LASP u32x4_t*)(ls + VOFF + ((tid >> 3) + 64 * c) * VR + (tid & 7) * 16) = vreg[c];
;         __syncthreads();
;     ...
;         for (int kp = 0; kp < NKP; ++kp) {
;             bf16x8_t pb[2];
; #pragma unroll
;             for (int qg = 0; qg < 2; ++qg) {
;                 const f32x4_t a = s[2 * kp][qg], b = s[2 * kp + 1][qg];
;                 u32x4_t pk; pk.x = pg8::cvt_pk_bf16(a[0], a[1]); pk.y = pg8::cvt_pk_bf16(a[2], a[3]); pk.z = pg8::cvt_pk_bf16(b[0], b[1]); pk.w = pg8::cvt_pk_bf16(b[2], b[3]);
;                 pb[qg] = __builtin_bit_cast(bf16x8_t, pk);
;             }
; #pragma unroll
;             for (int dg = 0; dg < 4; ++dg) {
;                 LASP unsigned char* va = ls + VOFF + (32 * kp + 4 * fq + (fr >> 2)) * VR + (16 * dg + 4 * (fr & 3)) * 2;
;                 const s16x4 v0 = __builtin_amdgcn_ds_read_tr16_b64_v4i16((LASP s16x4*)va);
;                 const s16x4 v1 = __builtin_amdgcn_ds_read_tr16_b64_v4i16((LASP s16x4*)(va + 16 * VR));
;                 const bf16x8_t vf = __builtin_shufflevector(v0, v1, 0, 1, 2, 3, 4, 5, 6, 7);
;                 o[dg][0] = __builtin_amdgcn_mfma_f32_16x16x32_bf16(vf, pb[0], o[dg][0], 0, 0, 0);
;                 o[dg][1] = __builtin_amdgcn_mfma_f32_16x16x32_bf16(vf, pb[1], o[dg][1], 0, 0, 0);
;             }
;         }
	v_mfma_f32_16x16x32_bf16 v[134:137], v[66:69], v[102:105], 0
	v_mfma_f32_16x16x32_bf16 v[54:57], v[66:69], v[106:109], 0
	s_waitcnt lgkmcnt(2)
	v_mfma_f32_16x16x32_bf16 v[66:69], v[130:133], v[102:105], 0
	ds_read_b64_tr_b16 v[102:103], v226 offset:37408
	ds_read_b64_tr_b16 v[104:105], v226 offset:39712
	v_mfma_f32_16x16x32_bf16 v[130:133], v[130:133], v[106:109], 0
	v_cvt_pk_bf16_f32 v106, v170, v76
	v_cvt_pk_bf16_f32 v107, v80, v78
	v_cvt_pk_bf16_f32 v108, v84, v82
	v_cvt_pk_bf16_f32 v109, v88, v86
	s_waitcnt lgkmcnt(0)
	v_mfma_f32_16x16x32_bf16 v[110:113], v[102:105], v[138:141], v[110:113]
	v_mfma_f32_16x16x32_bf16 v[228:231], v[50:53], v[106:109], v[114:117]
	s_nop 2
	v_exp_f32_e32 v116, v49
	ds_read_b64_tr_b16 v[46:47], v226 offset:37440
	ds_read_b64_tr_b16 v[48:49], v226 offset:39744
	ds_read_b64_tr_b16 v[232:233], v226 offset:37472
	ds_read_b64_tr_b16 v[234:235], v226 offset:39776
	v_mfma_f32_16x16x32_bf16 v[50:53], v[50:53], v[138:141], v[120:123]
	v_exp_f32_e32 v114, v37
	v_mfma_f32_16x16x32_bf16 v[120:123], v[102:105], v[106:109], v[124:127]
	v_exp_f32_e32 v104, v39
	v_exp_f32_e32 v102, v40
	v_mov_b32_e32 v103, v222
	s_waitcnt lgkmcnt(2)
	v_mfma_f32_16x16x32_bf16 v[134:137], v[46:49], v[106:109], v[134:137]
	v_exp_f32_e32 v126, v34
	v_exp_f32_e32 v124, v30
	v_mfma_f32_16x16x32_bf16 v[42:45], v[46:49], v[138:141], v[54:57]
	s_waitcnt lgkmcnt(0)
	v_mfma_f32_16x16x32_bf16 v[46:49], v[232:235], v[106:109], v[66:69]
	v_exp_f32_e32 v106, v41
	ds_read_b64_tr_b16 v[38:39], v226 offset:41984
	ds_read_b64_tr_b16 v[40:41], v226 offset:44288
	v_cvt_pk_bf16_f32 v66, v96, v70
	v_mfma_f32_16x16x32_bf16 v[54:57], v[232:235], v[138:141], v[130:133]
	ds_read_b64_tr_b16 v[138:139], v226 offset:42016
	ds_read_b64_tr_b16 v[140:141], v226 offset:44320
	ds_read_b64_tr_b16 v[34:35], v226 offset:42048
	ds_read_b64_tr_b16 v[36:37], v226 offset:44352
	v_cvt_pk_bf16_f32 v67, v72, v74
	v_cvt_pk_bf16_f32 v68, v94, v92
	v_cvt_pk_bf16_f32 v69, v100, v116
	v_cvt_pk_bf16_f32 v232, v184, v182
	v_cvt_pk_bf16_f32 v233, v168, v166
	v_cvt_pk_bf16_f32 v234, v172, v104
	v_cvt_pk_bf16_f32 v235, v102, v106
	s_waitcnt lgkmcnt(2)
	v_mfma_f32_16x16x32_bf16 v[236:239], v[138:141], v[66:69], v[120:123]
	v_exp_f32_e32 v130, v32
	v_exp_f32_e32 v132, v33
	v_exp_f32_e32 v108, v23
	v_exp_f32_e32 v122, v31
	ds_read_b64_tr_b16 v[30:31], v226 offset:42080
	ds_read_b64_tr_b16 v[32:33], v226 offset:44384
	s_waitcnt lgkmcnt(2)
	v_mfma_f32_16x16x32_bf16 v[244:247], v[34:37], v[66:69], v[134:137]
	v_exp_f32_e32 v120, v24
	v_mfma_f32_16x16x32_bf16 v[34:37], v[34:37], v[232:235], v[42:45]
	s_nop 2
	ds_read_b64_tr_b16 v[42:43], v226 offset:46592
	ds_read_b64_tr_b16 v[44:45], v226 offset:48896
	v_exp_f32_e32 v136, v27
	v_exp_f32_e32 v134, v28
	v_mfma_f32_16x16x32_bf16 v[228:231], v[38:41], v[66:69], v[228:231]
	v_mfma_f32_16x16x32_bf16 v[240:243], v[138:141], v[232:235], v[110:113]
	v_exp_f32_e32 v140, v26
	v_exp_f32_e32 v138, v29
	s_nop 0
	v_exp_f32_e32 v110, v22
	v_exp_f32_e32 v112, v25
	v_mfma_f32_16x16x32_bf16 v[38:41], v[38:41], v[232:235], v[50:53]
	s_waitcnt lgkmcnt(2)
	v_mfma_f32_16x16x32_bf16 v[26:29], v[30:33], v[66:69], v[46:49]
	v_cvt_pk_bf16_f32 v66, v140, v136
	v_cvt_pk_bf16_f32 v67, v134, v138
	v_cvt_pk_bf16_f32 v68, v110, v108
	v_mfma_f32_16x16x32_bf16 v[54:57], v[30:33], v[232:235], v[54:57]
	v_cvt_pk_bf16_f32 v30, v126, v90
	v_cvt_pk_bf16_f32 v31, v98, v114
	v_cvt_pk_bf16_f32 v32, v124, v122
	v_cvt_pk_bf16_f32 v33, v130, v132
	v_cvt_pk_bf16_f32 v69, v120, v112
	s_waitcnt lgkmcnt(0)
	v_mfma_f32_16x16x32_bf16 v[46:49], v[42:45], v[30:33], v[228:231]
	ds_read_b64_tr_b16 v[22:23], v226 offset:46624
	ds_read_b64_tr_b16 v[24:25], v226 offset:48928
	s_nop 0
	ds_read_b64_tr_b16 v[228:229], v226 offset:46656
	ds_read_b64_tr_b16 v[230:231], v226 offset:48960
	v_mfma_f32_16x16x32_bf16 v[50:53], v[42:45], v[66:69], v[38:41]
	s_waitcnt lgkmcnt(2)
	v_mfma_f32_16x16x32_bf16 v[38:41], v[22:25], v[30:33], v[236:239]
	v_mfma_f32_16x16x32_bf16 v[42:45], v[22:25], v[66:69], v[240:243]
	v_mad_i64_i32 v[22:23], s[16:17], v64, s90, v[60:61]
	s_mov_b64 s[16:17], 0x90300
	s_nop 0
	v_lshl_add_u64 v[64:65], v[58:59], 0, s[16:17]
	v_add_co_u32_e32 v58, vcc, s5, v58
	global_load_dwordx4 v[232:235], v[22:23], off
	s_nop 0
	v_addc_co_u32_e32 v59, vcc, 0, v59, vcc
	s_waitcnt lgkmcnt(0)
	v_mfma_f32_16x16x32_bf16 v[22:25], v[228:231], v[30:33], v[244:247]
	ds_read_b64_tr_b16 v[236:237], v226 offset:46688
	ds_read_b64_tr_b16 v[238:239], v226 offset:48992
	s_mul_hi_u32 s5, s3, 0xa00
	s_mulk_i32 s3, 0xa00
	v_mfma_f32_16x16x32_bf16 v[34:37], v[228:231], v[66:69], v[34:37]
	global_load_dwordx4 v[58:61], v[58:59], off offset:768
	s_nop 0
	global_load_dwordx4 v[228:231], v[64:65], off offset:64
	global_load_dwordx4 v[240:243], v[146:147], off
	s_waitcnt lgkmcnt(0)
	v_mfma_f32_16x16x32_bf16 v[30:33], v[236:239], v[30:33], v[26:29]
	s_barrier
	s_waitcnt vmcnt(2)
	ds_write_b128 v63, v[58:61]
	s_waitcnt vmcnt(1)
	ds_write_b128 v63, v[228:231] offset:64
	ds_write_b128 v62, v[232:235] offset:32768
	s_waitcnt vmcnt(0)
	ds_write_b128 v62, v[240:243] offset:41984
	v_mfma_f32_16x16x32_bf16 v[26:29], v[236:239], v[66:69], v[54:57]
	s_waitcnt lgkmcnt(0)
	s_barrier
; #define LASP __attribute__((address_space(3)))
; template <int DQK>
; __device__ __forceinline__ void flash_item(unsigned char* smem, const bf16_t* Q, int qs, const bf16_t* K0, const bf16_t* V0, int n0, const bf16_t* K1, const bf16_t* V1, int n1, int ks, int vs, bf16_t* Oo, int os, float shift) {
;     ...
;         f32x4_t s[NKG][2];
; #pragma unroll
;         for (int kg = 0; kg < NKG; ++kg) { s[kg][0] = (f32x4_t){nsh, nsh, nsh, nsh}; s[kg][1] = (f32x4_t){nsh, nsh, nsh, nsh}; }
; #pragma unroll
;         for (int kk = 0; kk < NKK; ++kk) {
; #pragma unroll
;             for (int kg = 0; kg < NKG; ++kg) {
;                 const bf16x8_t kf = *(const LASP bf16x8_t*)(ls + (kg * 16 + fr) * KR + (kk * 32 + fq * 8) * 2);
;                 s[kg][0] = __builtin_amdgcn_mfma_f32_16x16x32_bf16(kf, qf[0][kk], s[kg][0], 0, 0, 0);
;                 s[kg][1] = __builtin_amdgcn_mfma_f32_16x16x32_bf16(kf, qf[1][kk], s[kg][1], 0, 0, 0);
;             }
;             asm volatile("" ::: "memory");
;         }
;         if (t + 1 < ntiles) FL_LOAD((t + 1) * KT);
; #pragma unroll
;         for (int qg = 0; qg < 2; ++qg) {
;             float ps = 0.f;
; #pragma unroll
;             for (int kg = 0; kg < NKG; ++kg)
; #pragma unroll
;                 for (int j = 0; j < 4; ++j) { const float p = __builtin_amdgcn_exp2f(s[kg][qg][j]); s[kg][qg][j] = p; ps += p; }
;             lsum[qg] += ps;
;         }
	s_nop 0
	ds_read_b128 v[54:57], v71
	ds_read_b128 v[62:65], v71 offset:2304
	s_waitcnt lgkmcnt(0)
	v_mfma_f32_16x16x32_bf16 v[66:69], v[62:65], v[10:13], v[18:21]
	s_add_u32 s3, s66, s3
	s_addc_u32 s5, s67, s5
	s_add_u32 s2, s3, s2
	v_mfma_f32_16x16x32_bf16 v[228:231], v[62:65], v[14:17], v[18:21]
	ds_read_b128 v[62:65], v71 offset:4608
	s_addc_u32 s3, s5, 0
	s_waitcnt lgkmcnt(0)
	v_mfma_f32_16x16x32_bf16 v[232:235], v[62:65], v[10:13], v[18:21]
	v_mfma_f32_16x16x32_bf16 v[236:239], v[62:65], v[14:17], v[18:21]
	ds_read_b128 v[62:65], v71 offset:6912
	s_waitcnt lgkmcnt(0)
	v_mfma_f32_16x16x32_bf16 v[240:243], v[62:65], v[10:13], v[18:21]
	v_mfma_f32_16x16x32_bf16 v[244:247], v[62:65], v[14:17], v[18:21]
	ds_read_b128 v[62:65], v71 offset:9216
	s_waitcnt lgkmcnt(0)
	v_mfma_f32_16x16x32_bf16 v[248:251], v[62:65], v[10:13], v[18:21]
	v_mfma_f32_16x16x32_bf16 v[146:149], v[62:65], v[14:17], v[18:21]
	ds_read_b128 v[62:65], v71 offset:11520
	s_waitcnt lgkmcnt(0)
	v_mfma_f32_16x16x32_bf16 v[150:153], v[62:65], v[10:13], v[18:21]
	v_mfma_f32_16x16x32_bf16 v[212:215], v[62:65], v[14:17], v[18:21]
	ds_read_b128 v[62:65], v71 offset:13824
	s_waitcnt lgkmcnt(0)
	v_mfma_f32_16x16x32_bf16 v[218:221], v[62:65], v[10:13], v[18:21]
	v_mfma_f32_16x16x32_bf16 v[206:209], v[62:65], v[14:17], v[18:21]
	ds_read_b128 v[62:65], v71 offset:16128
	v_mfma_f32_16x16x32_bf16 v[58:61], v[54:57], v[10:13], v[18:21]
	v_mfma_f32_16x16x32_bf16 v[54:57], v[54:57], v[14:17], v[18:21]
	s_waitcnt lgkmcnt(0)
	v_mfma_f32_16x16x32_bf16 v[10:13], v[62:65], v[10:13], v[18:21]
	v_mfma_f32_16x16x32_bf16 v[14:17], v[62:65], v[14:17], v[18:21]
	s_nop 2
	ds_read_b128 v[18:21], v71 offset:64
	s_waitcnt lgkmcnt(0)
	v_mfma_f32_16x16x32_bf16 v[222:225], v[18:21], v[6:9], v[58:61]
	s_nop 7
	v_exp_f32_e32 v143, v222
	v_mfma_f32_16x16x32_bf16 v[62:65], v[18:21], v[2:5], v[54:57]
	ds_read_b128 v[18:21], v71 offset:2368
	v_exp_f32_e32 v157, v223
	v_exp_f32_e32 v145, v224
	s_waitcnt lgkmcnt(0)
	v_mfma_f32_16x16x32_bf16 v[54:57], v[18:21], v[6:9], v[66:69]
	v_exp_f32_e32 v161, v225
	v_add_f32_e32 v222, 0, v75
	s_nop 0
	v_exp_f32_e32 v197, v62
	v_mfma_f32_16x16x32_bf16 v[66:69], v[18:21], v[2:5], v[228:231]
	ds_read_b128 v[18:21], v71 offset:4672
	s_nop 1
	v_exp_f32_e32 v159, v54
	v_exp_f32_e32 v165, v55
	s_waitcnt lgkmcnt(0)
	v_mfma_f32_16x16x32_bf16 v[232:235], v[18:21], v[6:9], v[232:235]
	v_exp_f32_e32 v163, v56
	v_exp_f32_e32 v171, v57
	v_exp_f32_e32 v199, v63
	v_mfma_f32_16x16x32_bf16 v[58:61], v[18:21], v[2:5], v[236:239]
	ds_read_b128 v[18:21], v71 offset:6976
	s_nop 2
	v_exp_f32_e32 v77, v232
	v_exp_f32_e32 v81, v233
	s_waitcnt lgkmcnt(0)
	v_mfma_f32_16x16x32_bf16 v[236:239], v[18:21], v[6:9], v[240:243]
	v_exp_f32_e32 v79, v234
	v_exp_f32_e32 v85, v235
	v_exp_f32_e32 v189, v64
	v_mfma_f32_16x16x32_bf16 v[228:231], v[18:21], v[2:5], v[244:247]
	ds_read_b128 v[18:21], v71 offset:9280
	s_nop 2
	v_exp_f32_e32 v83, v236
	v_exp_f32_e32 v89, v237
	s_waitcnt lgkmcnt(0)
	v_mfma_f32_16x16x32_bf16 v[240:243], v[18:21], v[6:9], v[248:251]
	v_exp_f32_e32 v87, v238
	v_exp_f32_e32 v97, v239
	v_exp_f32_e32 v193, v65
	v_mfma_f32_16x16x32_bf16 v[18:21], v[18:21], v[2:5], v[146:149]
	s_nop 3
	v_exp_f32_e32 v75, v242
	v_exp_f32_e32 v95, v243
	v_mov_b32_e32 v223, v0
	ds_read_b128 v[146:149], v71 offset:11584
	s_waitcnt lgkmcnt(0)
	v_mfma_f32_16x16x32_bf16 v[244:247], v[146:149], v[6:9], v[150:153]
	v_exp_f32_e32 v191, v66
	v_exp_f32_e32 v195, v67
	v_exp_f32_e32 v201, v68
	v_mfma_f32_16x16x32_bf16 v[150:153], v[146:149], v[2:5], v[212:215]
	ds_read_b128 v[146:149], v71 offset:13888
	s_nop 2
	v_exp_f32_e32 v93, v244
	v_exp_f32_e32 v101, v245
	s_waitcnt lgkmcnt(0)
	v_mfma_f32_16x16x32_bf16 v[212:215], v[146:149], v[6:9], v[218:221]
	s_nop 2
	ds_read_b128 v[218:221], v71 offset:16192
	v_exp_f32_e32 v71, v240
	v_exp_f32_e32 v117, v246
	v_mfma_f32_16x16x32_bf16 v[146:149], v[146:149], v[2:5], v[206:209]
	v_exp_f32_e32 v127, v247
	v_exp_f32_e32 v91, v212
	v_exp_f32_e32 v99, v213
	v_add_f32_e32 v206, 0, v73
	v_mov_b32_e32 v207, v0
	s_waitcnt lgkmcnt(0)
	v_mfma_f32_16x16x32_bf16 v[6:9], v[218:221], v[6:9], v[10:13]
	v_exp_f32_e32 v73, v241
	v_exp_f32_e32 v115, v214
	v_exp_f32_e32 v125, v215
	v_pk_add_f32 v[10:11], v[142:143], v[206:207]
	s_nop 3
	v_exp_f32_e32 v123, v6
	v_pk_add_f32 v[10:11], v[156:157], v[10:11]
	v_exp_f32_e32 v131, v7
	v_pk_add_f32 v[10:11], v[144:145], v[10:11]
	v_exp_f32_e32 v133, v8
	v_pk_add_f32 v[10:11], v[160:161], v[10:11]
	v_exp_f32_e32 v1, v9
	v_pk_add_f32 v[10:11], v[158:159], v[10:11]
	v_exp_f32_e32 v203, v69
	v_pk_add_f32 v[10:11], v[164:165], v[10:11]
	v_mfma_f32_16x16x32_bf16 v[2:5], v[218:221], v[2:5], v[14:17]
	v_add_f32_e64 v10, v162, v10
	v_add_f32_e64 v11, v163, v11
	v_cvt_pk_bf16_f32 v12, v159, v165
	v_pk_add_f32 v[10:11], v[170:171], v[10:11]
	v_cvt_pk_bf16_f32 v13, v163, v171
	v_pk_add_f32 v[10:11], v[76:77], v[10:11]
	v_cvt_pk_bf16_f32 v14, v197, v199
	v_pk_add_f32 v[10:11], v[80:81], v[10:11]
	v_cvt_pk_bf16_f32 v15, v189, v193
	v_pk_add_f32 v[10:11], v[78:79], v[10:11]
	v_cvt_pk_bf16_f32 v16, v191, v195
	v_pk_add_f32 v[10:11], v[84:85], v[10:11]
	v_cvt_pk_bf16_f32 v17, v201, v203
	v_pk_add_f32 v[10:11], v[82:83], v[10:11]
	v_exp_f32_e32 v187, v58
	v_pk_add_f32 v[10:11], v[88:89], v[10:11]
	v_exp_f32_e32 v179, v59
	v_pk_add_f32 v[10:11], v[86:87], v[10:11]
	v_exp_f32_e32 v177, v60
	v_pk_add_f32 v[10:11], v[96:97], v[10:11]
	v_exp_f32_e32 v181, v61
	v_pk_add_f32 v[10:11], v[70:71], v[10:11]
	v_exp_f32_e32 v175, v228
	v_pk_add_f32 v[10:11], v[72:73], v[10:11]
	v_exp_f32_e32 v119, v229
	v_pk_add_f32 v[10:11], v[74:75], v[10:11]
	v_exp_f32_e32 v129, v230
; __device__ __forceinline__ unsigned cvt_pk_bf16(float lo, float hi) { const f32x2c f = {lo, hi}; return __builtin_bit_cast(unsigned, __builtin_convertvector(f, bf16x2c)); }
; #define LASP __attribute__((address_space(3)))
; template <int DQK>
; __device__ __forceinline__ void flash_item(unsigned char* smem, const bf16_t* Q, int qs, const bf16_t* K0, const bf16_t* V0, int n0, const bf16_t* K1, const bf16_t* V1, int n1, int ks, int vs, bf16_t* Oo, int os, float shift) {
;     ...
;         for (int qg = 0; qg < 2; ++qg) {
;             float ps = 0.f;
; #pragma unroll
;             for (int kg = 0; kg < NKG; ++kg)
; #pragma unroll
;                 for (int j = 0; j < 4; ++j) { const float p = __builtin_amdgcn_exp2f(s[kg][qg][j]); s[kg][qg][j] = p; ps += p; }
;             lsum[qg] += ps;
;         }
; #pragma unroll
;         for (int kp = 0; kp < NKP; ++kp) {
;             bf16x8_t pb[2];
; #pragma unroll
;             for (int qg = 0; qg < 2; ++qg) {
;                 const f32x4_t a = s[2 * kp][qg], b = s[2 * kp + 1][qg];
;                 u32x4_t pk; pk.x = pg8::cvt_pk_bf16(a[0], a[1]); pk.y = pg8::cvt_pk_bf16(a[2], a[3]); pk.z = pg8::cvt_pk_bf16(b[0], b[1]); pk.w = pg8::cvt_pk_bf16(b[2], b[3]);
;                 pb[qg] = __builtin_bit_cast(bf16x8_t, pk);
;             }
; #pragma unroll
;             for (int dg = 0; dg < 4; ++dg) {
;                 LASP unsigned char* va = ls + VOFF + (32 * kp + 4 * fq + (fr >> 2)) * VR + (16 * dg + 4 * (fr & 3)) * 2;
;                 const s16x4 v0 = __builtin_amdgcn_ds_read_tr16_b64_v4i16((LASP s16x4*)va);
;                 const s16x4 v1 = __builtin_amdgcn_ds_read_tr16_b64_v4i16((LASP s16x4*)(va + 16 * VR));
;                 const bf16x8_t vf = __builtin_shufflevector(v0, v1, 0, 1, 2, 3, 4, 5, 6, 7);
;                 o[dg][0] = __builtin_amdgcn_mfma_f32_16x16x32_bf16(vf, pb[0], o[dg][0], 0, 0, 0);
;                 o[dg][1] = __builtin_amdgcn_mfma_f32_16x16x32_bf16(vf, pb[1], o[dg][1], 0, 0, 0);
;             }
;         }
	v_pk_add_f32 v[10:11], v[94:95], v[10:11]
	v_exp_f32_e32 v185, v231
	v_pk_add_f32 v[6:7], v[92:93], v[10:11]
	v_exp_f32_e32 v183, v18
	v_pk_add_f32 v[6:7], v[100:101], v[6:7]
	v_exp_f32_e32 v169, v19
	v_pk_add_f32 v[6:7], v[116:117], v[6:7]
	v_exp_f32_e32 v167, v20
	v_pk_add_f32 v[6:7], v[126:127], v[6:7]
	v_exp_f32_e32 v173, v21
	v_pk_add_f32 v[6:7], v[90:91], v[6:7]
	v_exp_f32_e32 v105, v150
	v_pk_add_f32 v[6:7], v[98:99], v[6:7]
	v_exp_f32_e32 v107, v152
	v_pk_add_f32 v[6:7], v[114:115], v[6:7]
	v_exp_f32_e32 v141, v153
	v_pk_add_f32 v[6:7], v[124:125], v[6:7]
	v_exp_f32_e32 v137, v146
	v_pk_add_f32 v[6:7], v[122:123], v[6:7]
	v_exp_f32_e32 v135, v147
	v_pk_add_f32 v[6:7], v[130:131], v[6:7]
	v_exp_f32_e32 v139, v148
	v_pk_add_f32 v[6:7], v[132:133], v[6:7]
	v_exp_f32_e32 v111, v149
	v_pk_add_f32 v[6:7], v[0:1], v[6:7]
	v_exp_f32_e32 v109, v2
	v_add_f32_e32 v70, v6, v7
	v_pk_add_f32 v[6:7], v[196:197], v[222:223]
	v_mov_b32_e32 v222, v103
	v_pk_add_f32 v[6:7], v[198:199], v[6:7]
	v_exp_f32_e32 v103, v151
	v_pk_add_f32 v[6:7], v[188:189], v[6:7]
	v_exp_f32_e32 v121, v3
	v_pk_add_f32 v[6:7], v[192:193], v[6:7]
	v_exp_f32_e32 v113, v4
	v_pk_add_f32 v[6:7], v[190:191], v[6:7]
	s_nop 0
	v_pk_add_f32 v[10:11], v[194:195], v[6:7]
	ds_read_b64_tr_b16 v[8:9], v226 offset:35072
	ds_read_b64_tr_b16 v[6:7], v226 offset:32768
	ds_read_b64_tr_b16 v[54:55], v226 offset:32800
	ds_read_b64_tr_b16 v[56:57], v226 offset:35104
	v_pk_add_f32 v[62:63], v[200:201], v[10:11]
	v_cvt_pk_bf16_f32 v10, v143, v157
	v_cvt_pk_bf16_f32 v11, v145, v161
	s_waitcnt lgkmcnt(0)
	v_mfma_f32_16x16x32_bf16 v[42:45], v[54:57], v[14:17], v[42:45]
	v_add_f32_e64 v62, v202, v62
	v_add_f32_e64 v63, v203, v63
	v_pk_add_f32 v[62:63], v[186:187], v[62:63]
	v_mfma_f32_16x16x32_bf16 v[46:49], v[6:9], v[10:13], v[46:49]
	v_mfma_f32_16x16x32_bf16 v[6:9], v[6:9], v[14:17], v[50:53]
	s_nop 2
	ds_read_b64_tr_b16 v[50:51], v226 offset:32832
	ds_read_b64_tr_b16 v[52:53], v226 offset:35136
	v_mfma_f32_16x16x32_bf16 v[38:41], v[54:57], v[10:13], v[38:41]
	ds_read_b64_tr_b16 v[54:55], v226 offset:32864
	ds_read_b64_tr_b16 v[56:57], v226 offset:35168
	s_waitcnt lgkmcnt(2)
	v_mfma_f32_16x16x32_bf16 v[22:25], v[50:53], v[10:13], v[22:25]
	v_mfma_f32_16x16x32_bf16 v[34:37], v[50:53], v[14:17], v[34:37]
	v_cvt_pk_bf16_f32 v50, v187, v179
	v_cvt_pk_bf16_f32 v51, v177, v181
	v_cvt_pk_bf16_f32 v52, v175, v119
	s_waitcnt lgkmcnt(0)
	v_mfma_f32_16x16x32_bf16 v[10:13], v[54:57], v[10:13], v[30:33]
	s_nop 2
	ds_read_b64_tr_b16 v[30:31], v226 offset:37376
	ds_read_b64_tr_b16 v[32:33], v226 offset:39680
	v_cvt_pk_bf16_f32 v53, v129, v185
	v_mfma_f32_16x16x32_bf16 v[14:17], v[54:57], v[14:17], v[26:29]
	ds_read_b64_tr_b16 v[54:55], v226 offset:37408
	ds_read_b64_tr_b16 v[56:57], v226 offset:39712
	ds_read_b64_tr_b16 v[18:19], v226 offset:37440
	ds_read_b64_tr_b16 v[20:21], v226 offset:39744
	v_cvt_pk_bf16_f32 v26, v77, v81
	v_cvt_pk_bf16_f32 v27, v79, v85
	v_cvt_pk_bf16_f32 v28, v83, v89
	v_cvt_pk_bf16_f32 v29, v87, v97
	s_waitcnt lgkmcnt(4)
	v_mfma_f32_16x16x32_bf16 v[6:9], v[30:33], v[50:53], v[6:9]
	v_mfma_f32_16x16x32_bf16 v[46:49], v[30:33], v[26:29], v[46:49]
	s_waitcnt lgkmcnt(2)
	v_mfma_f32_16x16x32_bf16 v[30:33], v[54:57], v[26:29], v[38:41]
	s_nop 2
	v_add_f32_e64 v38, v178, v62
	v_add_f32_e64 v39, v179, v63
	s_waitcnt lgkmcnt(0)
	v_mfma_f32_16x16x32_bf16 v[22:25], v[18:21], v[26:29], v[22:25]
	v_add_f32_e64 v38, v176, v38
	v_add_f32_e64 v39, v177, v39
	v_pk_add_f32 v[58:59], v[180:181], v[38:39]
	v_mfma_f32_16x16x32_bf16 v[38:41], v[54:57], v[50:53], v[42:45]
	s_nop 2
	ds_read_b64_tr_b16 v[42:43], v226 offset:37472
	ds_read_b64_tr_b16 v[44:45], v226 offset:39776
	v_pk_add_f32 v[54:55], v[174:175], v[58:59]
	v_exp_f32_e32 v57, v5
	v_mfma_f32_16x16x32_bf16 v[18:21], v[18:21], v[50:53], v[34:37]
	v_add_f32_e64 v54, v118, v54
	v_add_f32_e64 v55, v119, v55
	v_mov_b32_e32 v56, v0
	v_pk_add_f32 v[54:55], v[128:129], v[54:55]
	s_waitcnt lgkmcnt(0)
	v_mfma_f32_16x16x32_bf16 v[10:13], v[42:45], v[26:29], v[10:13]
	ds_read_b64_tr_b16 v[26:27], v226 offset:41984
	ds_read_b64_tr_b16 v[28:29], v226 offset:44288
	v_cvt_pk_bf16_f32 v34, v71, v73
	v_cvt_pk_bf16_f32 v35, v75, v95
	v_mfma_f32_16x16x32_bf16 v[14:17], v[42:45], v[50:53], v[14:17]
	ds_read_b64_tr_b16 v[50:51], v226 offset:42016
	ds_read_b64_tr_b16 v[52:53], v226 offset:44320
	v_cvt_pk_bf16_f32 v36, v93, v101
	v_cvt_pk_bf16_f32 v37, v117, v127
	v_cvt_pk_bf16_f32 v42, v183, v169
	v_cvt_pk_bf16_f32 v43, v167, v173
	v_cvt_pk_bf16_f32 v44, v105, v103
	v_cvt_pk_bf16_f32 v45, v107, v141
	s_waitcnt lgkmcnt(2)
	v_mfma_f32_16x16x32_bf16 v[46:49], v[26:29], v[34:37], v[46:49]
	v_add_f32_e64 v54, v184, v54
	v_add_f32_e64 v55, v185, v55
	v_pk_add_f32 v[54:55], v[182:183], v[54:55]
	v_mfma_f32_16x16x32_bf16 v[6:9], v[26:29], v[42:45], v[6:9]
	ds_read_b64_tr_b16 v[26:27], v226 offset:42048
	ds_read_b64_tr_b16 v[28:29], v226 offset:44352
	v_pk_add_f32 v[54:55], v[168:169], v[54:55]
	s_waitcnt lgkmcnt(2)
; template <int K> __device__ __forceinline__ float swz(float v) { return __int_as_float(__builtin_amdgcn_ds_swizzle(__float_as_int(v), (K << 10) | 0x1f)); }
; __device__ __forceinline__ float x32_sum(float v) { auto r = __builtin_amdgcn_permlane32_swap(__float_as_uint(v), __float_as_uint(v), false, false); return __uint_as_float(r[0]) + __uint_as_float(r[1]); }
; #define LASP __attribute__((address_space(3)))
; template <int DQK>
; __device__ __forceinline__ void flash_item(unsigned char* smem, const bf16_t* Q, int qs, const bf16_t* K0, const bf16_t* V0, int n0, const bf16_t* K1, const bf16_t* V1, int n1, int ks, int vs, bf16_t* Oo, int os, float shift) {
;     ...
;         for (int kp = 0; kp < NKP; ++kp) {
;             bf16x8_t pb[2];
; #pragma unroll
;             for (int qg = 0; qg < 2; ++qg) {
;                 const f32x4_t a = s[2 * kp][qg], b = s[2 * kp + 1][qg];
;                 u32x4_t pk; pk.x = pg8::cvt_pk_bf16(a[0], a[1]); pk.y = pg8::cvt_pk_bf16(a[2], a[3]); pk.z = pg8::cvt_pk_bf16(b[0], b[1]); pk.w = pg8::cvt_pk_bf16(b[2], b[3]);
;                 pb[qg] = __builtin_bit_cast(bf16x8_t, pk);
;             }
; #pragma unroll
;             for (int dg = 0; dg < 4; ++dg) {
;                 LASP unsigned char* va = ls + VOFF + (32 * kp + 4 * fq + (fr >> 2)) * VR + (16 * dg + 4 * (fr & 3)) * 2;
;                 const s16x4 v0 = __builtin_amdgcn_ds_read_tr16_b64_v4i16((LASP s16x4*)va);
;                 const s16x4 v1 = __builtin_amdgcn_ds_read_tr16_b64_v4i16((LASP s16x4*)(va + 16 * VR));
;                 const bf16x8_t vf = __builtin_shufflevector(v0, v1, 0, 1, 2, 3, 4, 5, 6, 7);
;                 o[dg][0] = __builtin_amdgcn_mfma_f32_16x16x32_bf16(vf, pb[0], o[dg][0], 0, 0, 0);
;                 o[dg][1] = __builtin_amdgcn_mfma_f32_16x16x32_bf16(vf, pb[1], o[dg][1], 0, 0, 0);
;             }
;         }
;     }
;     ...
; #pragma unroll
;     for (int qg = 0; qg < 2; ++qg) {
;         float l = lsum[qg]; l += swz<16>(l); l = x32_sum(l);
;         const float inv = 1.0f / l;
;         bf16_t* orow = Oo + (size_t)(wave * 32 + qg * 16 + fr) * os + fq * 4;
; #pragma unroll
;         for (int dg = 0; dg < 4; ++dg) {
;             u32x2_t w; w.x = pg8::cvt_pk_bf16(o[dg][qg][0] * inv, o[dg][qg][1] * inv); w.y = pg8::cvt_pk_bf16(o[dg][qg][2] * inv, o[dg][qg][3] * inv);
;             *(u32x2_t*)(orow + dg * 16) = w;
;         }
	v_mfma_f32_16x16x32_bf16 v[30:33], v[50:53], v[34:37], v[30:33]
	v_add_f32_e64 v54, v166, v54
	v_add_f32_e64 v55, v167, v55
	v_pk_add_f32 v[54:55], v[172:173], v[54:55]
	v_mfma_f32_16x16x32_bf16 v[38:41], v[50:53], v[42:45], v[38:41]
	ds_read_b64_tr_b16 v[50:51], v226 offset:42080
	ds_read_b64_tr_b16 v[52:53], v226 offset:44384
	ds_read_b64_tr_b16 v[2:3], v226 offset:46592
	ds_read_b64_tr_b16 v[4:5], v226 offset:48896
	s_waitcnt lgkmcnt(4)
	v_mfma_f32_16x16x32_bf16 v[22:25], v[26:29], v[34:37], v[22:25]
	v_mfma_f32_16x16x32_bf16 v[18:21], v[26:29], v[42:45], v[18:21]
	s_waitcnt lgkmcnt(2)
	v_mfma_f32_16x16x32_bf16 v[10:13], v[50:53], v[34:37], v[10:13]
	v_cvt_pk_bf16_f32 v34, v91, v99
	v_cvt_pk_bf16_f32 v35, v115, v125
	v_cvt_pk_bf16_f32 v36, v123, v131
	v_mfma_f32_16x16x32_bf16 v[26:29], v[50:53], v[42:45], v[14:17]
	v_cvt_pk_bf16_f32 v37, v133, v1
	v_cvt_pk_bf16_f32 v42, v137, v135
	ds_read_b64_tr_b16 v[50:51], v226 offset:46624
	ds_read_b64_tr_b16 v[52:53], v226 offset:48928
	v_cvt_pk_bf16_f32 v43, v139, v111
	v_cvt_pk_bf16_f32 v44, v109, v121
	v_cvt_pk_bf16_f32 v45, v113, v57
	s_waitcnt lgkmcnt(2)
	v_mfma_f32_16x16x32_bf16 v[46:49], v[2:5], v[34:37], v[46:49]
	ds_swizzle_b32 v1, v70 offset:swizzle(SWAP,16)
	s_waitcnt lgkmcnt(0)
	v_add_f32_e32 v1, v70, v1
	v_mfma_f32_16x16x32_bf16 v[14:17], v[2:5], v[42:45], v[6:9]
	v_add_f32_e64 v2, v104, v54
	v_add_f32_e64 v3, v105, v55
	s_nop 0
	ds_read_b64_tr_b16 v[6:7], v226 offset:46656
	ds_read_b64_tr_b16 v[8:9], v226 offset:48960
	v_pk_add_f32 v[2:3], v[102:103], v[2:3]
	v_mfma_f32_16x16x32_bf16 v[30:33], v[50:53], v[34:37], v[30:33]
	v_add_f32_e64 v2, v106, v2
	v_add_f32_e64 v3, v107, v3
	v_pk_add_f32 v[54:55], v[140:141], v[2:3]
	v_mfma_f32_16x16x32_bf16 v[2:5], v[50:53], v[42:45], v[38:41]
	s_nop 2
	v_add_f32_e64 v38, v136, v54
	v_add_f32_e64 v39, v137, v55
	s_waitcnt lgkmcnt(0)
	v_mfma_f32_16x16x32_bf16 v[22:25], v[6:9], v[34:37], v[22:25]
	v_add_f32_e64 v38, v134, v38
	v_add_f32_e64 v39, v135, v39
	v_pk_add_f32 v[50:51], v[138:139], v[38:39]
	ds_read_b64_tr_b16 v[38:39], v226 offset:46688
	ds_read_b64_tr_b16 v[40:41], v226 offset:48992
	v_pk_add_f32 v[50:51], v[110:111], v[50:51]
	v_mfma_f32_16x16x32_bf16 v[6:9], v[6:9], v[42:45], v[18:21]
	v_add_f32_e64 v50, v108, v50
	v_add_f32_e64 v51, v109, v51
	v_pk_add_f32 v[50:51], v[120:121], v[50:51]
	s_nop 0
	v_pk_add_f32 v[18:19], v[112:113], v[50:51]
	s_nop 0
	v_pk_add_f32 v[50:51], v[56:57], v[18:19]
	s_waitcnt lgkmcnt(0)
	v_mfma_f32_16x16x32_bf16 v[18:21], v[38:41], v[34:37], v[10:13]
	v_add_f32_e32 v50, v50, v51
	s_nop 1
	v_mov_b32_e32 v10, v1
	s_nop 1
	v_permlane32_swap_b32_e32 v1, v10
	v_add_f32_e32 v1, v1, v10
	v_div_scale_f32 v34, s[16:17], v1, v1, 1.0
	v_rcp_f32_e32 v35, v34
	v_mfma_f32_16x16x32_bf16 v[10:13], v[38:41], v[42:45], v[26:29]
	s_nop 2
	v_fma_f32 v28, -v34, v35, 1.0
	v_fmac_f32_e32 v35, v28, v35
	v_div_scale_f32 v28, vcc, 1.0, v1, 1.0
	v_mul_f32_e32 v29, v28, v35
	v_fma_f32 v36, -v34, v29, v28
	v_fmac_f32_e32 v29, v36, v35
	v_fma_f32 v28, -v34, v29, v28
	v_div_fmas_f32 v28, v28, v35, v29
	v_div_fixup_f32 v28, v28, v1, 1.0
	ds_swizzle_b32 v1, v50 offset:swizzle(SWAP,16)
	v_pk_mul_f32 v[18:19], v[18:19], v[28:29] op_sel_hi:[1,0]
	v_lshl_add_u64 v[26:27], s[2:3], 0, v[204:205]
	v_cvt_pk_bf16_f32 v86, v18, v19
	v_pk_mul_f32 v[22:23], v[22:23], v[28:29] op_sel_hi:[1,0]
	s_waitcnt lgkmcnt(0)
	v_add_f32_e32 v1, v50, v1
	v_mov_b32_e32 v19, v1
	v_pk_mul_f32 v[24:25], v[24:25], v[28:29] op_sel_hi:[1,0]
	s_nop 0
	v_permlane32_swap_b32_e32 v1, v19
	v_mad_i64_i32 v[34:35], s[2:3], v211, s93, v[26:27]
	v_cvt_pk_bf16_f32 v84, v22, v23
	v_cvt_pk_bf16_f32 v85, v24, v25
	v_add_f32_e32 v1, v1, v19
	v_div_scale_f32 v22, s[2:3], v1, v1, 1.0
	v_rcp_f32_e32 v23, v22
	v_pk_mul_f32 v[20:21], v[20:21], v[28:29] op_sel_hi:[1,0]
	v_pk_mul_f32 v[36:37], v[46:47], v[28:29] op_sel_hi:[1,0]
	v_cvt_pk_bf16_f32 v87, v20, v21
	v_fma_f32 v18, -v22, v23, 1.0
	v_fmac_f32_e32 v23, v18, v23
	v_div_scale_f32 v18, vcc, 1.0, v1, 1.0
	v_mul_f32_e32 v19, v18, v23
	v_fma_f32 v20, -v22, v19, v18
	v_fmac_f32_e32 v19, v20, v23
	v_fma_f32 v18, -v22, v19, v18
	v_div_fmas_f32 v18, v18, v23, v19
	v_div_fixup_f32 v18, v18, v1, 1.0
	v_pk_mul_f32 v[38:39], v[48:49], v[28:29] op_sel_hi:[1,0]
	v_pk_mul_f32 v[30:31], v[30:31], v[28:29] op_sel_hi:[1,0]
	v_pk_mul_f32 v[32:33], v[32:33], v[28:29] op_sel_hi:[1,0]
	v_pk_mul_f32 v[14:15], v[14:15], v[18:19] op_sel_hi:[1,0]
	v_pk_mul_f32 v[16:17], v[16:17], v[18:19] op_sel_hi:[1,0]
	v_mov_b32_e32 v211, v216
	v_cvt_pk_bf16_f32 v88, v36, v37
	v_cvt_pk_bf16_f32 v89, v38, v39
	v_cvt_pk_bf16_f32 v90, v30, v31
	v_cvt_pk_bf16_f32 v91, v32, v33
	v_mad_i64_i32 v[20:21], s[2:3], v227, s93, v[26:27]
	v_cvt_pk_bf16_f32 v148, v14, v15
	v_cvt_pk_bf16_f32 v149, v16, v17
	v_and_b32_e32 v96, 16, v253
	v_lshrrev_b32_e32 v98, 1, v96
	v_add_u32_e32 v96, v96, v98
	v_mov_b32_e32 v97, 0
	v_permlane16_swap_b32_e32 v88, v90
	v_permlane16_swap_b32_e32 v89, v91
	v_permlane16_swap_b32_e32 v84, v86
	v_permlane16_swap_b32_e32 v85, v87
	v_lshl_add_u64 v[34:35], v[34:35], 0, v[96:97]
	global_store_dwordx4 v[34:35], v[88:91], off
	global_store_dwordx4 v[34:35], v[84:87], off offset:64
